# adaLN GEMV item: all 128 weight-row loads issued before the accumulate (was 16 serialized batches of 8)
# speedup vs baseline: 1.0922x; 1.0011x over previous
.LBB0_20:
	v_lshlrev_b32_e32 v28, 2, v8
	s_mov_b64 s[24:25], s[0:1]
	global_load_dword v60, v28, s[24:25]
	s_add_u32 s24, s24, 0x6000
	s_addc_u32 s25, s25, 0
	global_load_dword v61, v28, s[24:25]
	s_add_u32 s24, s24, 0x6000
	s_addc_u32 s25, s25, 0
	global_load_dword v62, v28, s[24:25]
	s_add_u32 s24, s24, 0x6000
	s_addc_u32 s25, s25, 0
	global_load_dword v63, v28, s[24:25]
	s_add_u32 s24, s24, 0x6000
	s_addc_u32 s25, s25, 0
	global_load_dword v64, v28, s[24:25]
	s_add_u32 s24, s24, 0x6000
	s_addc_u32 s25, s25, 0
	global_load_dword v65, v28, s[24:25]
	s_add_u32 s24, s24, 0x6000
	s_addc_u32 s25, s25, 0
	global_load_dword v66, v28, s[24:25]
	s_add_u32 s24, s24, 0x6000
	s_addc_u32 s25, s25, 0
	global_load_dword v67, v28, s[24:25]
	s_add_u32 s24, s24, 0x6000
	s_addc_u32 s25, s25, 0
	global_load_dword v68, v28, s[24:25]
	s_add_u32 s24, s24, 0x6000
	s_addc_u32 s25, s25, 0
	global_load_dword v69, v28, s[24:25]
	s_add_u32 s24, s24, 0x6000
	s_addc_u32 s25, s25, 0
	global_load_dword v70, v28, s[24:25]
	s_add_u32 s24, s24, 0x6000
	s_addc_u32 s25, s25, 0
	global_load_dword v71, v28, s[24:25]
	s_add_u32 s24, s24, 0x6000
	s_addc_u32 s25, s25, 0
	global_load_dword v72, v28, s[24:25]
	s_add_u32 s24, s24, 0x6000
	s_addc_u32 s25, s25, 0
	global_load_dword v73, v28, s[24:25]
	s_add_u32 s24, s24, 0x6000
	s_addc_u32 s25, s25, 0
	global_load_dword v74, v28, s[24:25]
	s_add_u32 s24, s24, 0x6000
	s_addc_u32 s25, s25, 0
	global_load_dword v75, v28, s[24:25]
	s_add_u32 s24, s24, 0x6000
	s_addc_u32 s25, s25, 0
	global_load_dword v76, v28, s[24:25]
	s_add_u32 s24, s24, 0x6000
	s_addc_u32 s25, s25, 0
	global_load_dword v77, v28, s[24:25]
	s_add_u32 s24, s24, 0x6000
	s_addc_u32 s25, s25, 0
	global_load_dword v78, v28, s[24:25]
	s_add_u32 s24, s24, 0x6000
	s_addc_u32 s25, s25, 0
	global_load_dword v79, v28, s[24:25]
	s_add_u32 s24, s24, 0x6000
	s_addc_u32 s25, s25, 0
	global_load_dword v80, v28, s[24:25]
	s_add_u32 s24, s24, 0x6000
	s_addc_u32 s25, s25, 0
	global_load_dword v81, v28, s[24:25]
	s_add_u32 s24, s24, 0x6000
	s_addc_u32 s25, s25, 0
	global_load_dword v82, v28, s[24:25]
	s_add_u32 s24, s24, 0x6000
	s_addc_u32 s25, s25, 0
	global_load_dword v83, v28, s[24:25]
	s_add_u32 s24, s24, 0x6000
	s_addc_u32 s25, s25, 0
	global_load_dword v84, v28, s[24:25]
	s_add_u32 s24, s24, 0x6000
	s_addc_u32 s25, s25, 0
	global_load_dword v85, v28, s[24:25]
	s_add_u32 s24, s24, 0x6000
	s_addc_u32 s25, s25, 0
	global_load_dword v86, v28, s[24:25]
	s_add_u32 s24, s24, 0x6000
	s_addc_u32 s25, s25, 0
	global_load_dword v87, v28, s[24:25]
	s_add_u32 s24, s24, 0x6000
	s_addc_u32 s25, s25, 0
	global_load_dword v88, v28, s[24:25]
	s_add_u32 s24, s24, 0x6000
	s_addc_u32 s25, s25, 0
	global_load_dword v89, v28, s[24:25]
	s_add_u32 s24, s24, 0x6000
	s_addc_u32 s25, s25, 0
	global_load_dword v90, v28, s[24:25]
	s_add_u32 s24, s24, 0x6000
	s_addc_u32 s25, s25, 0
	global_load_dword v91, v28, s[24:25]
	s_add_u32 s24, s24, 0x6000
	s_addc_u32 s25, s25, 0
	global_load_dword v92, v28, s[24:25]
	s_add_u32 s24, s24, 0x6000
	s_addc_u32 s25, s25, 0
	global_load_dword v93, v28, s[24:25]
	s_add_u32 s24, s24, 0x6000
	s_addc_u32 s25, s25, 0
	global_load_dword v94, v28, s[24:25]
	s_add_u32 s24, s24, 0x6000
	s_addc_u32 s25, s25, 0
	global_load_dword v95, v28, s[24:25]
	s_add_u32 s24, s24, 0x6000
	s_addc_u32 s25, s25, 0
	global_load_dword v96, v28, s[24:25]
	s_add_u32 s24, s24, 0x6000
	s_addc_u32 s25, s25, 0
	global_load_dword v97, v28, s[24:25]
	s_add_u32 s24, s24, 0x6000
	s_addc_u32 s25, s25, 0
	global_load_dword v98, v28, s[24:25]
	s_add_u32 s24, s24, 0x6000
	s_addc_u32 s25, s25, 0
	global_load_dword v99, v28, s[24:25]
	s_add_u32 s24, s24, 0x6000
	s_addc_u32 s25, s25, 0
	global_load_dword v100, v28, s[24:25]
	s_add_u32 s24, s24, 0x6000
	s_addc_u32 s25, s25, 0
	global_load_dword v101, v28, s[24:25]
	s_add_u32 s24, s24, 0x6000
	s_addc_u32 s25, s25, 0
	global_load_dword v102, v28, s[24:25]
	s_add_u32 s24, s24, 0x6000
	s_addc_u32 s25, s25, 0
	global_load_dword v103, v28, s[24:25]
	s_add_u32 s24, s24, 0x6000
	s_addc_u32 s25, s25, 0
	global_load_dword v104, v28, s[24:25]
	s_add_u32 s24, s24, 0x6000
	s_addc_u32 s25, s25, 0
	global_load_dword v105, v28, s[24:25]
	s_add_u32 s24, s24, 0x6000
	s_addc_u32 s25, s25, 0
	global_load_dword v106, v28, s[24:25]
	s_add_u32 s24, s24, 0x6000
	s_addc_u32 s25, s25, 0
	global_load_dword v107, v28, s[24:25]
	s_add_u32 s24, s24, 0x6000
	s_addc_u32 s25, s25, 0
	global_load_dword v108, v28, s[24:25]
	s_add_u32 s24, s24, 0x6000
	s_addc_u32 s25, s25, 0
	global_load_dword v109, v28, s[24:25]
	s_add_u32 s24, s24, 0x6000
	s_addc_u32 s25, s25, 0
	global_load_dword v110, v28, s[24:25]
	s_add_u32 s24, s24, 0x6000
	s_addc_u32 s25, s25, 0
	global_load_dword v111, v28, s[24:25]
	s_add_u32 s24, s24, 0x6000
	s_addc_u32 s25, s25, 0
	global_load_dword v112, v28, s[24:25]
	s_add_u32 s24, s24, 0x6000
	s_addc_u32 s25, s25, 0
	global_load_dword v113, v28, s[24:25]
	s_add_u32 s24, s24, 0x6000
	s_addc_u32 s25, s25, 0
	global_load_dword v114, v28, s[24:25]
	s_add_u32 s24, s24, 0x6000
	s_addc_u32 s25, s25, 0
	global_load_dword v115, v28, s[24:25]
	s_add_u32 s24, s24, 0x6000
	s_addc_u32 s25, s25, 0
	global_load_dword v116, v28, s[24:25]
	s_add_u32 s24, s24, 0x6000
	s_addc_u32 s25, s25, 0
	global_load_dword v117, v28, s[24:25]
	s_add_u32 s24, s24, 0x6000
	s_addc_u32 s25, s25, 0
	global_load_dword v118, v28, s[24:25]
	s_add_u32 s24, s24, 0x6000
	s_addc_u32 s25, s25, 0
	global_load_dword v119, v28, s[24:25]
	s_add_u32 s24, s24, 0x6000
	s_addc_u32 s25, s25, 0
	global_load_dword v120, v28, s[24:25]
	s_add_u32 s24, s24, 0x6000
	s_addc_u32 s25, s25, 0
	global_load_dword v121, v28, s[24:25]
	s_add_u32 s24, s24, 0x6000
	s_addc_u32 s25, s25, 0
	global_load_dword v122, v28, s[24:25]
	s_add_u32 s24, s24, 0x6000
	s_addc_u32 s25, s25, 0
	global_load_dword v123, v28, s[24:25]
	s_add_u32 s24, s24, 0x6000
	s_addc_u32 s25, s25, 0
	global_load_dword v124, v28, s[24:25]
	s_add_u32 s24, s24, 0x6000
	s_addc_u32 s25, s25, 0
	global_load_dword v125, v28, s[24:25]
	s_add_u32 s24, s24, 0x6000
	s_addc_u32 s25, s25, 0
	global_load_dword v126, v28, s[24:25]
	s_add_u32 s24, s24, 0x6000
	s_addc_u32 s25, s25, 0
	global_load_dword v127, v28, s[24:25]
	s_add_u32 s24, s24, 0x6000
	s_addc_u32 s25, s25, 0
	global_load_dword v128, v28, s[24:25]
	s_add_u32 s24, s24, 0x6000
	s_addc_u32 s25, s25, 0
	global_load_dword v129, v28, s[24:25]
	s_add_u32 s24, s24, 0x6000
	s_addc_u32 s25, s25, 0
	global_load_dword v130, v28, s[24:25]
	s_add_u32 s24, s24, 0x6000
	s_addc_u32 s25, s25, 0
	global_load_dword v131, v28, s[24:25]
	s_add_u32 s24, s24, 0x6000
	s_addc_u32 s25, s25, 0
	global_load_dword v132, v28, s[24:25]
	s_add_u32 s24, s24, 0x6000
	s_addc_u32 s25, s25, 0
	global_load_dword v133, v28, s[24:25]
	s_add_u32 s24, s24, 0x6000
	s_addc_u32 s25, s25, 0
	global_load_dword v134, v28, s[24:25]
	s_add_u32 s24, s24, 0x6000
	s_addc_u32 s25, s25, 0
	global_load_dword v135, v28, s[24:25]
	s_add_u32 s24, s24, 0x6000
	s_addc_u32 s25, s25, 0
	global_load_dword v136, v28, s[24:25]
	s_add_u32 s24, s24, 0x6000
	s_addc_u32 s25, s25, 0
	global_load_dword v137, v28, s[24:25]
	s_add_u32 s24, s24, 0x6000
	s_addc_u32 s25, s25, 0
	global_load_dword v138, v28, s[24:25]
	s_add_u32 s24, s24, 0x6000
	s_addc_u32 s25, s25, 0
	global_load_dword v139, v28, s[24:25]
	s_add_u32 s24, s24, 0x6000
	s_addc_u32 s25, s25, 0
	global_load_dword v140, v28, s[24:25]
	s_add_u32 s24, s24, 0x6000
	s_addc_u32 s25, s25, 0
	global_load_dword v141, v28, s[24:25]
	s_add_u32 s24, s24, 0x6000
	s_addc_u32 s25, s25, 0
	global_load_dword v142, v28, s[24:25]
	s_add_u32 s24, s24, 0x6000
	s_addc_u32 s25, s25, 0
	global_load_dword v143, v28, s[24:25]
	s_add_u32 s24, s24, 0x6000
	s_addc_u32 s25, s25, 0
	global_load_dword v144, v28, s[24:25]
	s_add_u32 s24, s24, 0x6000
	s_addc_u32 s25, s25, 0
	global_load_dword v145, v28, s[24:25]
	s_add_u32 s24, s24, 0x6000
	s_addc_u32 s25, s25, 0
	global_load_dword v146, v28, s[24:25]
	s_add_u32 s24, s24, 0x6000
	s_addc_u32 s25, s25, 0
	global_load_dword v147, v28, s[24:25]
	s_add_u32 s24, s24, 0x6000
	s_addc_u32 s25, s25, 0
	global_load_dword v148, v28, s[24:25]
	s_add_u32 s24, s24, 0x6000
	s_addc_u32 s25, s25, 0
	global_load_dword v149, v28, s[24:25]
	s_add_u32 s24, s24, 0x6000
	s_addc_u32 s25, s25, 0
	global_load_dword v150, v28, s[24:25]
	s_add_u32 s24, s24, 0x6000
	s_addc_u32 s25, s25, 0
	global_load_dword v151, v28, s[24:25]
	s_add_u32 s24, s24, 0x6000
	s_addc_u32 s25, s25, 0
	global_load_dword v152, v28, s[24:25]
	s_add_u32 s24, s24, 0x6000
	s_addc_u32 s25, s25, 0
	global_load_dword v153, v28, s[24:25]
	s_add_u32 s24, s24, 0x6000
	s_addc_u32 s25, s25, 0
	global_load_dword v154, v28, s[24:25]
	s_add_u32 s24, s24, 0x6000
	s_addc_u32 s25, s25, 0
	global_load_dword v155, v28, s[24:25]
	s_add_u32 s24, s24, 0x6000
	s_addc_u32 s25, s25, 0
	global_load_dword v156, v28, s[24:25]
	s_add_u32 s24, s24, 0x6000
	s_addc_u32 s25, s25, 0
	global_load_dword v157, v28, s[24:25]
	s_add_u32 s24, s24, 0x6000
	s_addc_u32 s25, s25, 0
	global_load_dword v158, v28, s[24:25]
	s_add_u32 s24, s24, 0x6000
	s_addc_u32 s25, s25, 0
	global_load_dword v159, v28, s[24:25]
	s_add_u32 s24, s24, 0x6000
	s_addc_u32 s25, s25, 0
	global_load_dword v160, v28, s[24:25]
	s_add_u32 s24, s24, 0x6000
	s_addc_u32 s25, s25, 0
	global_load_dword v161, v28, s[24:25]
	s_add_u32 s24, s24, 0x6000
	s_addc_u32 s25, s25, 0
	global_load_dword v162, v28, s[24:25]
	s_add_u32 s24, s24, 0x6000
	s_addc_u32 s25, s25, 0
	global_load_dword v163, v28, s[24:25]
	s_add_u32 s24, s24, 0x6000
	s_addc_u32 s25, s25, 0
	global_load_dword v164, v28, s[24:25]
	s_add_u32 s24, s24, 0x6000
	s_addc_u32 s25, s25, 0
	global_load_dword v165, v28, s[24:25]
	s_add_u32 s24, s24, 0x6000
	s_addc_u32 s25, s25, 0
	global_load_dword v166, v28, s[24:25]
	s_add_u32 s24, s24, 0x6000
	s_addc_u32 s25, s25, 0
	global_load_dword v167, v28, s[24:25]
	s_add_u32 s24, s24, 0x6000
	s_addc_u32 s25, s25, 0
	global_load_dword v168, v28, s[24:25]
	s_add_u32 s24, s24, 0x6000
	s_addc_u32 s25, s25, 0
	global_load_dword v169, v28, s[24:25]
	s_add_u32 s24, s24, 0x6000
	s_addc_u32 s25, s25, 0
	global_load_dword v170, v28, s[24:25]
	s_add_u32 s24, s24, 0x6000
	s_addc_u32 s25, s25, 0
	global_load_dword v171, v28, s[24:25]
	s_add_u32 s24, s24, 0x6000
	s_addc_u32 s25, s25, 0
	global_load_dword v172, v28, s[24:25]
	s_add_u32 s24, s24, 0x6000
	s_addc_u32 s25, s25, 0
	global_load_dword v173, v28, s[24:25]
	s_add_u32 s24, s24, 0x6000
	s_addc_u32 s25, s25, 0
	global_load_dword v174, v28, s[24:25]
	s_add_u32 s24, s24, 0x6000
	s_addc_u32 s25, s25, 0
	global_load_dword v175, v28, s[24:25]
	s_add_u32 s24, s24, 0x6000
	s_addc_u32 s25, s25, 0
	global_load_dword v176, v28, s[24:25]
	s_add_u32 s24, s24, 0x6000
	s_addc_u32 s25, s25, 0
	global_load_dword v177, v28, s[24:25]
	s_add_u32 s24, s24, 0x6000
	s_addc_u32 s25, s25, 0
	global_load_dword v178, v28, s[24:25]
	s_add_u32 s24, s24, 0x6000
	s_addc_u32 s25, s25, 0
	global_load_dword v179, v28, s[24:25]
	s_add_u32 s24, s24, 0x6000
	s_addc_u32 s25, s25, 0
	global_load_dword v180, v28, s[24:25]
	s_add_u32 s24, s24, 0x6000
	s_addc_u32 s25, s25, 0
	global_load_dword v181, v28, s[24:25]
	s_add_u32 s24, s24, 0x6000
	s_addc_u32 s25, s25, 0
	global_load_dword v182, v28, s[24:25]
	s_add_u32 s24, s24, 0x6000
	s_addc_u32 s25, s25, 0
	global_load_dword v183, v28, s[24:25]
	s_add_u32 s24, s24, 0x6000
	s_addc_u32 s25, s25, 0
	global_load_dword v184, v28, s[24:25]
	s_add_u32 s24, s24, 0x6000
	s_addc_u32 s25, s25, 0
	global_load_dword v185, v28, s[24:25]
	s_add_u32 s24, s24, 0x6000
	s_addc_u32 s25, s25, 0
	global_load_dword v186, v28, s[24:25]
	s_add_u32 s24, s24, 0x6000
	s_addc_u32 s25, s25, 0
	global_load_dword v187, v28, s[24:25]
	v_mov_b32_e32 v29, 0
	ds_read_b128 v[190:193], v29 offset:0
	ds_read_b128 v[194:197], v29 offset:16
	ds_read_b128 v[198:201], v29 offset:32
	ds_read_b128 v[202:205], v29 offset:48
	ds_read_b128 v[206:209], v29 offset:64
	ds_read_b128 v[210:213], v29 offset:80
	ds_read_b128 v[214:217], v29 offset:96
	ds_read_b128 v[218:221], v29 offset:112
	ds_read_b128 v[222:225], v29 offset:512
	ds_read_b128 v[226:229], v29 offset:528
	ds_read_b128 v[230:233], v29 offset:544
	ds_read_b128 v[234:237], v29 offset:560
	ds_read_b128 v[238:241], v29 offset:576
	ds_read_b128 v[242:245], v29 offset:592
	ds_read_b128 v[246:249], v29 offset:608
	ds_read_b128 v[250:253], v29 offset:624
	s_waitcnt vmcnt(63)
	s_waitcnt lgkmcnt(0)
	v_fmac_f32_e32 v11, v190, v60
	v_fmac_f32_e32 v10, v222, v60
	v_fmac_f32_e32 v11, v191, v61
	v_fmac_f32_e32 v10, v223, v61
	v_fmac_f32_e32 v11, v192, v62
	v_fmac_f32_e32 v10, v224, v62
	v_fmac_f32_e32 v11, v193, v63
	v_fmac_f32_e32 v10, v225, v63
	v_fmac_f32_e32 v11, v194, v64
	v_fmac_f32_e32 v10, v226, v64
	v_fmac_f32_e32 v11, v195, v65
	v_fmac_f32_e32 v10, v227, v65
	v_fmac_f32_e32 v11, v196, v66
	v_fmac_f32_e32 v10, v228, v66
	v_fmac_f32_e32 v11, v197, v67
	v_fmac_f32_e32 v10, v229, v67
	v_fmac_f32_e32 v11, v198, v68
	v_fmac_f32_e32 v10, v230, v68
	v_fmac_f32_e32 v11, v199, v69
	v_fmac_f32_e32 v10, v231, v69
	v_fmac_f32_e32 v11, v200, v70
	v_fmac_f32_e32 v10, v232, v70
	v_fmac_f32_e32 v11, v201, v71
	v_fmac_f32_e32 v10, v233, v71
	v_fmac_f32_e32 v11, v202, v72
	v_fmac_f32_e32 v10, v234, v72
	v_fmac_f32_e32 v11, v203, v73
	v_fmac_f32_e32 v10, v235, v73
	v_fmac_f32_e32 v11, v204, v74
	v_fmac_f32_e32 v10, v236, v74
	v_fmac_f32_e32 v11, v205, v75
	v_fmac_f32_e32 v10, v237, v75
	v_fmac_f32_e32 v11, v206, v76
	v_fmac_f32_e32 v10, v238, v76
	v_fmac_f32_e32 v11, v207, v77
	v_fmac_f32_e32 v10, v239, v77
	v_fmac_f32_e32 v11, v208, v78
	v_fmac_f32_e32 v10, v240, v78
	v_fmac_f32_e32 v11, v209, v79
	v_fmac_f32_e32 v10, v241, v79
	v_fmac_f32_e32 v11, v210, v80
	v_fmac_f32_e32 v10, v242, v80
	v_fmac_f32_e32 v11, v211, v81
	v_fmac_f32_e32 v10, v243, v81
	v_fmac_f32_e32 v11, v212, v82
	v_fmac_f32_e32 v10, v244, v82
	v_fmac_f32_e32 v11, v213, v83
	v_fmac_f32_e32 v10, v245, v83
	v_fmac_f32_e32 v11, v214, v84
	v_fmac_f32_e32 v10, v246, v84
	v_fmac_f32_e32 v11, v215, v85
	v_fmac_f32_e32 v10, v247, v85
	v_fmac_f32_e32 v11, v216, v86
	v_fmac_f32_e32 v10, v248, v86
	v_fmac_f32_e32 v11, v217, v87
	v_fmac_f32_e32 v10, v249, v87
	v_fmac_f32_e32 v11, v218, v88
	v_fmac_f32_e32 v10, v250, v88
	v_fmac_f32_e32 v11, v219, v89
	v_fmac_f32_e32 v10, v251, v89
	v_fmac_f32_e32 v11, v220, v90
	v_fmac_f32_e32 v10, v252, v90
	v_fmac_f32_e32 v11, v221, v91
	v_fmac_f32_e32 v10, v253, v91
	v_mov_b32_e32 v29, 128
	ds_read_b128 v[190:193], v29 offset:0
	ds_read_b128 v[194:197], v29 offset:16
	ds_read_b128 v[198:201], v29 offset:32
	ds_read_b128 v[202:205], v29 offset:48
	ds_read_b128 v[206:209], v29 offset:64
	ds_read_b128 v[210:213], v29 offset:80
	ds_read_b128 v[214:217], v29 offset:96
	ds_read_b128 v[218:221], v29 offset:112
	ds_read_b128 v[222:225], v29 offset:512
	ds_read_b128 v[226:229], v29 offset:528
	ds_read_b128 v[230:233], v29 offset:544
	ds_read_b128 v[234:237], v29 offset:560
	ds_read_b128 v[238:241], v29 offset:576
	ds_read_b128 v[242:245], v29 offset:592
	ds_read_b128 v[246:249], v29 offset:608
	ds_read_b128 v[250:253], v29 offset:624
	s_waitcnt vmcnt(63)
	s_waitcnt lgkmcnt(0)
	v_fmac_f32_e32 v11, v190, v92
	v_fmac_f32_e32 v10, v222, v92
	v_fmac_f32_e32 v11, v191, v93
	v_fmac_f32_e32 v10, v223, v93
	v_fmac_f32_e32 v11, v192, v94
	v_fmac_f32_e32 v10, v224, v94
	v_fmac_f32_e32 v11, v193, v95
	v_fmac_f32_e32 v10, v225, v95
	v_fmac_f32_e32 v11, v194, v96
	v_fmac_f32_e32 v10, v226, v96
	v_fmac_f32_e32 v11, v195, v97
	v_fmac_f32_e32 v10, v227, v97
	v_fmac_f32_e32 v11, v196, v98
	v_fmac_f32_e32 v10, v228, v98
	v_fmac_f32_e32 v11, v197, v99
	v_fmac_f32_e32 v10, v229, v99
	v_fmac_f32_e32 v11, v198, v100
	v_fmac_f32_e32 v10, v230, v100
	v_fmac_f32_e32 v11, v199, v101
	v_fmac_f32_e32 v10, v231, v101
	v_fmac_f32_e32 v11, v200, v102
	v_fmac_f32_e32 v10, v232, v102
	v_fmac_f32_e32 v11, v201, v103
	v_fmac_f32_e32 v10, v233, v103
	v_fmac_f32_e32 v11, v202, v104
	v_fmac_f32_e32 v10, v234, v104
	v_fmac_f32_e32 v11, v203, v105
	v_fmac_f32_e32 v10, v235, v105
	v_fmac_f32_e32 v11, v204, v106
	v_fmac_f32_e32 v10, v236, v106
	v_fmac_f32_e32 v11, v205, v107
	v_fmac_f32_e32 v10, v237, v107
	v_fmac_f32_e32 v11, v206, v108
	v_fmac_f32_e32 v10, v238, v108
	v_fmac_f32_e32 v11, v207, v109
	v_fmac_f32_e32 v10, v239, v109
	v_fmac_f32_e32 v11, v208, v110
	v_fmac_f32_e32 v10, v240, v110
	v_fmac_f32_e32 v11, v209, v111
	v_fmac_f32_e32 v10, v241, v111
	v_fmac_f32_e32 v11, v210, v112
	v_fmac_f32_e32 v10, v242, v112
	v_fmac_f32_e32 v11, v211, v113
	v_fmac_f32_e32 v10, v243, v113
	v_fmac_f32_e32 v11, v212, v114
	v_fmac_f32_e32 v10, v244, v114
	v_fmac_f32_e32 v11, v213, v115
	v_fmac_f32_e32 v10, v245, v115
	v_fmac_f32_e32 v11, v214, v116
	v_fmac_f32_e32 v10, v246, v116
	v_fmac_f32_e32 v11, v215, v117
	v_fmac_f32_e32 v10, v247, v117
	v_fmac_f32_e32 v11, v216, v118
	v_fmac_f32_e32 v10, v248, v118
	v_fmac_f32_e32 v11, v217, v119
	v_fmac_f32_e32 v10, v249, v119
	v_fmac_f32_e32 v11, v218, v120
	v_fmac_f32_e32 v10, v250, v120
	v_fmac_f32_e32 v11, v219, v121
	v_fmac_f32_e32 v10, v251, v121
	v_fmac_f32_e32 v11, v220, v122
	v_fmac_f32_e32 v10, v252, v122
	v_fmac_f32_e32 v11, v221, v123
	v_fmac_f32_e32 v10, v253, v123
	v_mov_b32_e32 v29, 256
	ds_read_b128 v[190:193], v29 offset:0
	ds_read_b128 v[194:197], v29 offset:16
	ds_read_b128 v[198:201], v29 offset:32
	ds_read_b128 v[202:205], v29 offset:48
	ds_read_b128 v[206:209], v29 offset:64
	ds_read_b128 v[210:213], v29 offset:80
	ds_read_b128 v[214:217], v29 offset:96
	ds_read_b128 v[218:221], v29 offset:112
	ds_read_b128 v[222:225], v29 offset:512
	ds_read_b128 v[226:229], v29 offset:528
	ds_read_b128 v[230:233], v29 offset:544
	ds_read_b128 v[234:237], v29 offset:560
	ds_read_b128 v[238:241], v29 offset:576
	ds_read_b128 v[242:245], v29 offset:592
	ds_read_b128 v[246:249], v29 offset:608
	ds_read_b128 v[250:253], v29 offset:624
	s_waitcnt vmcnt(32)
	s_waitcnt lgkmcnt(0)
	v_fmac_f32_e32 v11, v190, v124
	v_fmac_f32_e32 v10, v222, v124
	v_fmac_f32_e32 v11, v191, v125
	v_fmac_f32_e32 v10, v223, v125
	v_fmac_f32_e32 v11, v192, v126
	v_fmac_f32_e32 v10, v224, v126
	v_fmac_f32_e32 v11, v193, v127
	v_fmac_f32_e32 v10, v225, v127
	v_fmac_f32_e32 v11, v194, v128
	v_fmac_f32_e32 v10, v226, v128
	v_fmac_f32_e32 v11, v195, v129
	v_fmac_f32_e32 v10, v227, v129
	v_fmac_f32_e32 v11, v196, v130
	v_fmac_f32_e32 v10, v228, v130
	v_fmac_f32_e32 v11, v197, v131
	v_fmac_f32_e32 v10, v229, v131
	v_fmac_f32_e32 v11, v198, v132
	v_fmac_f32_e32 v10, v230, v132
	v_fmac_f32_e32 v11, v199, v133
	v_fmac_f32_e32 v10, v231, v133
	v_fmac_f32_e32 v11, v200, v134
	v_fmac_f32_e32 v10, v232, v134
	v_fmac_f32_e32 v11, v201, v135
	v_fmac_f32_e32 v10, v233, v135
	v_fmac_f32_e32 v11, v202, v136
	v_fmac_f32_e32 v10, v234, v136
	v_fmac_f32_e32 v11, v203, v137
	v_fmac_f32_e32 v10, v235, v137
	v_fmac_f32_e32 v11, v204, v138
	v_fmac_f32_e32 v10, v236, v138
	v_fmac_f32_e32 v11, v205, v139
	v_fmac_f32_e32 v10, v237, v139
	v_fmac_f32_e32 v11, v206, v140
	v_fmac_f32_e32 v10, v238, v140
	v_fmac_f32_e32 v11, v207, v141
	v_fmac_f32_e32 v10, v239, v141
	v_fmac_f32_e32 v11, v208, v142
	v_fmac_f32_e32 v10, v240, v142
	v_fmac_f32_e32 v11, v209, v143
	v_fmac_f32_e32 v10, v241, v143
	v_fmac_f32_e32 v11, v210, v144
	v_fmac_f32_e32 v10, v242, v144
	v_fmac_f32_e32 v11, v211, v145
	v_fmac_f32_e32 v10, v243, v145
	v_fmac_f32_e32 v11, v212, v146
	v_fmac_f32_e32 v10, v244, v146
	v_fmac_f32_e32 v11, v213, v147
	v_fmac_f32_e32 v10, v245, v147
	v_fmac_f32_e32 v11, v214, v148
	v_fmac_f32_e32 v10, v246, v148
	v_fmac_f32_e32 v11, v215, v149
	v_fmac_f32_e32 v10, v247, v149
	v_fmac_f32_e32 v11, v216, v150
	v_fmac_f32_e32 v10, v248, v150
	v_fmac_f32_e32 v11, v217, v151
	v_fmac_f32_e32 v10, v249, v151
	v_fmac_f32_e32 v11, v218, v152
	v_fmac_f32_e32 v10, v250, v152
	v_fmac_f32_e32 v11, v219, v153
	v_fmac_f32_e32 v10, v251, v153
	v_fmac_f32_e32 v11, v220, v154
	v_fmac_f32_e32 v10, v252, v154
	v_fmac_f32_e32 v11, v221, v155
	v_fmac_f32_e32 v10, v253, v155
	v_mov_b32_e32 v29, 384
	ds_read_b128 v[190:193], v29 offset:0
	ds_read_b128 v[194:197], v29 offset:16
	ds_read_b128 v[198:201], v29 offset:32
	ds_read_b128 v[202:205], v29 offset:48
	ds_read_b128 v[206:209], v29 offset:64
	ds_read_b128 v[210:213], v29 offset:80
	ds_read_b128 v[214:217], v29 offset:96
	ds_read_b128 v[218:221], v29 offset:112
	ds_read_b128 v[222:225], v29 offset:512
	ds_read_b128 v[226:229], v29 offset:528
	ds_read_b128 v[230:233], v29 offset:544
	ds_read_b128 v[234:237], v29 offset:560
	ds_read_b128 v[238:241], v29 offset:576
	ds_read_b128 v[242:245], v29 offset:592
	ds_read_b128 v[246:249], v29 offset:608
	ds_read_b128 v[250:253], v29 offset:624
	s_waitcnt vmcnt(0)
	s_waitcnt lgkmcnt(0)
	v_fmac_f32_e32 v11, v190, v156
	v_fmac_f32_e32 v10, v222, v156
	v_fmac_f32_e32 v11, v191, v157
	v_fmac_f32_e32 v10, v223, v157
	v_fmac_f32_e32 v11, v192, v158
	v_fmac_f32_e32 v10, v224, v158
	v_fmac_f32_e32 v11, v193, v159
	v_fmac_f32_e32 v10, v225, v159
	v_fmac_f32_e32 v11, v194, v160
	v_fmac_f32_e32 v10, v226, v160
	v_fmac_f32_e32 v11, v195, v161
	v_fmac_f32_e32 v10, v227, v161
	v_fmac_f32_e32 v11, v196, v162
	v_fmac_f32_e32 v10, v228, v162
	v_fmac_f32_e32 v11, v197, v163
	v_fmac_f32_e32 v10, v229, v163
	v_fmac_f32_e32 v11, v198, v164
	v_fmac_f32_e32 v10, v230, v164
	v_fmac_f32_e32 v11, v199, v165
	v_fmac_f32_e32 v10, v231, v165
	v_fmac_f32_e32 v11, v200, v166
	v_fmac_f32_e32 v10, v232, v166
	v_fmac_f32_e32 v11, v201, v167
	v_fmac_f32_e32 v10, v233, v167
	v_fmac_f32_e32 v11, v202, v168
	v_fmac_f32_e32 v10, v234, v168
	v_fmac_f32_e32 v11, v203, v169
	v_fmac_f32_e32 v10, v235, v169
	v_fmac_f32_e32 v11, v204, v170
	v_fmac_f32_e32 v10, v236, v170
	v_fmac_f32_e32 v11, v205, v171
	v_fmac_f32_e32 v10, v237, v171
	v_fmac_f32_e32 v11, v206, v172
	v_fmac_f32_e32 v10, v238, v172
	v_fmac_f32_e32 v11, v207, v173
	v_fmac_f32_e32 v10, v239, v173
	v_fmac_f32_e32 v11, v208, v174
	v_fmac_f32_e32 v10, v240, v174
	v_fmac_f32_e32 v11, v209, v175
	v_fmac_f32_e32 v10, v241, v175
	v_fmac_f32_e32 v11, v210, v176
	v_fmac_f32_e32 v10, v242, v176
	v_fmac_f32_e32 v11, v211, v177
	v_fmac_f32_e32 v10, v243, v177
	v_fmac_f32_e32 v11, v212, v178
	v_fmac_f32_e32 v10, v244, v178
	v_fmac_f32_e32 v11, v213, v179
	v_fmac_f32_e32 v10, v245, v179
	v_fmac_f32_e32 v11, v214, v180
	v_fmac_f32_e32 v10, v246, v180
	v_fmac_f32_e32 v11, v215, v181
	v_fmac_f32_e32 v10, v247, v181
	v_fmac_f32_e32 v11, v216, v182
	v_fmac_f32_e32 v10, v248, v182
	v_fmac_f32_e32 v11, v217, v183
	v_fmac_f32_e32 v10, v249, v183
	v_fmac_f32_e32 v11, v218, v184
	v_fmac_f32_e32 v10, v250, v184
	v_fmac_f32_e32 v11, v219, v185
	v_fmac_f32_e32 v10, v251, v185
	v_fmac_f32_e32 v11, v220, v186
	v_fmac_f32_e32 v10, v252, v186
	v_fmac_f32_e32 v11, v221, v187
	v_fmac_f32_e32 v10, v253, v187
	s_cmp_eq_u32 s10, 0
	s_cbranch_scc0 .LBB0_8
	s_mul_i32 s0, s22, 0x1800
	v_add_u32_e32 v12, s0, v8
	v_ashrrev_i32_e32 v13, 31, v12
	v_lshl_add_u64 v[12:13], v[12:13], 2, s[62:63]
	global_load_dword v2, v[12:13], off
	s_waitcnt vmcnt(0)
	v_pk_add_f32 v[10:11], v[10:11], v[2:3] op_sel_hi:[1,0]
	s_branch .LBB0_8
